# P1 idle workgroups convert a fifth weight item per wave (units 128-159), P2 keeps 4 weight units; plus deferred store-ack wait
# speedup vs baseline: 1.0039x; 1.0012x over previous
; #define LAS __attribute__((address_space(3)))
; __global__ void __launch_bounds__(NWAVES * 64, 2) fwd(Args args) {
;     ...
;     constexpr int NT1 = (M / 256) * (NIN / 256);
;     const int first_idle = NT1 - ((NT1 + G - 1) / G - 1) * G, w_p1 = (N_LAUNCHES == 1) ? ((G - first_idle) < N_W_UNITS ? (G - first_idle) : N_W_UNITS) : 0, w_p2 = N_W_UNITS - w_p1;
;     if (IN(1)) {
;         { pg8::Gemm g{XN, (const bf16*)(ws + WS_WIN), M, NIN, DM}; pg8::StaticOrder S; S.init(M, NIN, G, bx);
;           LAS float* rtab = (LAS float*)(lds + LDSCTL_OFF + 12288); int rpm = -1;
;           LAS float* gtab = (LAS float*)(lds + LDSCTL_OFF + 13824);
;           if (tid >= 256 && tid < 384) gtab[tid - 256] = tid < 320 ? args.in[4][tid - 256] : args.in[5][tid - 320];
.LBB0_121:
	s_add_u32 s28, s22, 0x4000000
	s_addc_u32 s29, s23, 0
	s_add_u32 s48, s22, 0x5000000
	s_addc_u32 s49, s23, 0
	s_add_u32 s66, s22, 0x6000000
	s_addc_u32 s67, s23, 0
	s_add_u32 s0, s22, 0x7000000
	s_addc_u32 s1, s23, 0
	v_writelane_b32 v254, s0, 34
	s_nop 1
	v_writelane_b32 v254, s1, 35
	s_abs_i32 s0, s33
	s_waitcnt vmcnt(0)
	v_cvt_f32_u32_e32 v1, s0
	s_sub_i32 s4, 0, s0
	s_add_i32 s1, s33, 0x27f
	s_xor_b32 s3, s1, s33
	v_rcp_iflag_f32_e32 v1, v1
	s_abs_i32 s1, s1
	s_ashr_i32 s3, s3, 31
	v_mul_f32_e32 v1, 0x4f7ffffe, v1
	v_cvt_u32_f32_e32 v1, v1
	s_nop 0
	v_readfirstlane_b32 s5, v1
	s_mul_i32 s4, s4, s5
	s_mul_hi_u32 s4, s5, s4
	s_add_i32 s5, s5, s4
	s_mul_hi_u32 s4, s1, s5
	s_mul_i32 s5, s4, s0
	s_sub_i32 s1, s1, s5
	s_add_i32 s6, s4, 1
	s_sub_i32 s5, s1, s0
	s_cmp_ge_u32 s1, s0
	s_cselect_b32 s4, s6, s4
	s_cselect_b32 s1, s5, s1
	s_add_i32 s5, s4, 1
	s_cmp_ge_u32 s1, s0
	s_cselect_b32 s0, s5, s4
	s_not_b32 s1, s3
	s_xor_b32 s0, s0, s3
	s_add_i32 s0, s1, s0
	s_mul_i32 s0, s0, s33
	s_sub_i32 s24, 0x280, s0
	s_sub_i32 s25, s33, s24
	s_min_i32 s30, s25, 0xa4
	s_cmpk_eq_i32 s25, 0x80
	s_cselect_b32 s30, 0xa0, s30
	s_cmp_lt_i32 s80, 2
	s_cselect_b64 s[0:1], -1, 0
	s_cmp_gt_i32 s81, 1
	s_cselect_b64 s[4:5], -1, 0
	s_and_b64 s[0:1], s[0:1], s[4:5]
	s_andn2_b64 vcc, exec, s[0:1]
	s_cbranch_vccnz .LBB0_339
	v_and_b32_e32 v1, 0x180, v0
	s_movk_i32 s0, 0x100
	v_cmp_eq_u32_e32 vcc, s0, v1
	s_and_saveexec_b64 s[0:1], vcc
	s_cbranch_execz .LBB0_124
	v_readlane_b32 s4, v254, 2
	v_readlane_b32 s5, v254, 3
	v_readlane_b32 s8, v254, 6
	v_readlane_b32 s9, v254, 7
	v_readlane_b32 s10, v254, 8
	v_readlane_b32 s11, v254, 9
	v_readlane_b32 s12, v254, 10
	v_readlane_b32 s13, v254, 11
	v_readlane_b32 s14, v254, 12
	v_readlane_b32 s15, v254, 13
	v_lshlrev_b32_e32 v2, 2, v0
	v_mov_b32_e32 v3, 0
	v_readlane_b32 s16, v254, 14
	v_readlane_b32 s17, v254, 15
	v_readlane_b32 s18, v254, 16
	v_readlane_b32 s19, v254, 17
	s_mov_b64 s[8:9], s[12:13]
	s_movk_i32 s4, 0xfc00
	v_lshl_add_u64 v[4:5], s[8:9], 0, v[2:3]
	s_mov_b32 s5, -1
	s_mov_b64 s[10:11], s[14:15]
	v_lshl_add_u64 v[4:5], v[4:5], 0, s[4:5]
	s_movk_i32 s4, 0xfb00
	s_movk_i32 s3, 0x140
	v_lshl_add_u64 v[6:7], s[10:11], 0, v[2:3]
	s_mov_b32 s5, -1
	v_lshl_add_u64 v[6:7], v[6:7], 0, s[4:5]
	v_cmp_gt_u32_e32 vcc, s3, v0
	s_add_i32 s3, 0, 0x23600
	v_add_u32_e32 v2, s3, v2
	v_cndmask_b32_e32 v5, v7, v5, vcc
	v_cndmask_b32_e32 v4, v6, v4, vcc
	global_load_dword v1, v[4:5], off
	v_add_u32_e32 v2, 0xfffffc00, v2
	v_readlane_b32 s6, v254, 4
	v_readlane_b32 s7, v254, 5
	s_mov_b64 s[12:13], s[16:17]
	s_mov_b64 s[14:15], s[18:19]
	s_waitcnt vmcnt(0)
	ds_write_b32 v2, v1

; #define LAS __attribute__((address_space(3)))
; __device__ __forceinline__ void transpose_item(const float* W, int ldw, int K, bf16* WT, int k0, int n0, int dst0, LAS float* scr, int lane, const float* rowgain = nullptr) {
;     float v[32];
; #pragma unroll
;     for (int i = 0; i < 32; ++i) { const int kk = 2 * i + (lane >> 5); v[i] = __builtin_nontemporal_load(&W[(size_t)(k0 + kk) * ldw + n0 + (lane & 31)]); }
;     if (rowgain) {
; #pragma unroll
;         for (int i = 0; i < 32; ++i) v[i] *= rowgain[k0 + 2 * i + (lane >> 5)]; }
; #pragma unroll
;     for (int i = 0; i < 32; ++i) scr[(2 * i + (lane >> 5)) * 33 + (lane & 31)] = v[i];
; __device__ __forceinline__ void weight_unit(int wu, const Args& a, LAS unsigned char* lds, int wave, int lane) {
;     asm volatile("" : "+v"(lane));
;     LAS float* scr = (LAS float*)(lds + RING_OFF + wave * 16384);
;     unsigned char* ws = a.ws;
;     for (int q = 0; q < 4; ++q) {
;         int r = wu * 32 + wave * 4 + q; if (r >= W_ITEMS) break;
;         if (r < WI_OUT) { const int kb = r / 32, nb = r % 32; transpose_item(a.in[15], DM, DM, (bf16*)(ws + WS_WOUT), 64 * kb, 32 * nb, 32 * nb, scr, lane); continue; } r -= WI_OUT;
;         if (r < WI_G) { const int kb = r / 88, nb = r % 88, n0 = 32 * nb; transpose_item(a.in[17], FF, DM, (bf16*)(ws + WS_WGU), 64 * kb, n0, 256 * (n0 >> 7) + (n0 & 127), scr, lane, a.in[16]); continue; } r -= WI_G;
;         if (r < WI_G) { const int kb = r / 88, nb = r % 88, n0 = 32 * nb; transpose_item(a.in[18], FF, DM, (bf16*)(ws + WS_WGU), 64 * kb, n0, 256 * (n0 >> 7) + 128 + (n0 & 127), scr, lane, a.in[16]); continue; } r -= WI_G;
; __global__ void __launch_bounds__(NWAVES * 64, 2) fwd(Args args) {
;     ...
;         if (w_p1 > 0 && bx >= first_idle && bx - first_idle < w_p1) weight_unit(bx - first_idle, args, lds, wave, lane);
.LBB0_241:
	s_or_b64 exec, exec, s[0:1]
	s_cmp_lt_i32 s25, 1
	s_cselect_b64 s[0:1], -1, 0
	s_cmp_lt_i32 s2, s24
	s_cselect_b64 s[4:5], -1, 0
	s_or_b64 s[0:1], s[4:5], s[0:1]
	v_readlane_b32 s4, v254, 18
	s_and_b64 vcc, exec, s[0:1]
	v_readlane_b32 s18, v254, 32
	v_readlane_b32 s19, v254, 33
	v_readlane_b32 s5, v254, 19
	v_readlane_b32 s6, v254, 20
	v_readlane_b32 s7, v254, 21
	v_readlane_b32 s8, v254, 22
	v_readlane_b32 s9, v254, 23
	v_readlane_b32 s10, v254, 24
	v_readlane_b32 s11, v254, 25
	v_readlane_b32 s12, v254, 26
	v_readlane_b32 s13, v254, 27
	v_readlane_b32 s14, v254, 28
	v_readlane_b32 s15, v254, 29
	v_readlane_b32 s16, v254, 30
	v_readlane_b32 s17, v254, 31
	s_cbranch_vccnz .LBB0_273
	s_sub_i32 s0, s2, s24
	s_cmp_ge_i32 s0, s30
	s_cbranch_scc1 .LBB0_273
	s_mov_b32 s32, s0
	s_mov_b32 s35, 4
	s_mov_b32 s52, 0
	s_mov_b32 s54, 0
.Lwu_again:
	s_lshl_b32 s10, s0, 5
	s_lshl_b32 s0, s76, 2
	s_add_i32 s10, s10, s0
	s_lshl_b32 s2, s76, 14
	s_lshl_b32 s0, s10, 1
	v_mov_b32_e32 v66, v206
	s_add_i32 s4, s2, 0
	s_and_b32 s2, s0, 0xffffffc0
	s_addk_i32 s2, 0xdb00
	v_ashrrev_i32_e32 v1, 5, v66
	v_lshlrev_b32_e32 v67, 2, v66
	s_movk_i32 s3, 0x84
	v_and_b32_e32 v146, 0x7c, v67
	v_mul_lo_u32 v67, v1, s3
	s_ashr_i32 s3, s2, 31
	v_add_u32_e32 v148, s2, v1
	v_ashrrev_i32_e32 v185, 3, v66
	v_lshlrev_b32_e32 v66, 3, v66
	s_lshl_b64 s[2:3], s[2:3], 1
	v_and_b32_e32 v66, 56, v66
	s_add_u32 s2, s22, s2
	s_addc_u32 s3, s23, s3
	v_lshlrev_b32_e32 v138, 1, v66
	v_mov_b32_e32 v139, 0
	v_add3_u32 v184, s4, v146, v67
	v_mul_u32_u24_e32 v68, 0x84, v66
	v_lshl_add_u64 v[66:67], s[2:3], 0, v[138:139]
	s_mov_b64 s[2:3], 0x1a00000
	s_and_b32 s0, s0, 0x3fc0
	v_lshl_add_u64 v[66:67], v[66:67], 0, s[2:3]
	v_lshlrev_b32_e32 v69, 2, v185
	s_add_i32 s2, s0, 0xffffe600
	v_add3_u32 v186, s4, v68, v69
	v_add_u32_e32 v68, s2, v1
	v_ashrrev_i32_e32 v69, 31, v68
	v_lshlrev_b64 v[68:69], 12, v[68:69]
	s_mov_b64 s[4:5], 0x2000
	v_lshl_add_u64 v[70:71], v[68:69], 0, s[4:5]
	s_mov_b64 s[4:5], 0x4000
	v_lshl_add_u64 v[72:73], v[68:69], 0, s[4:5]
	s_mov_b64 s[4:5], 0x6000
	v_lshl_add_u64 v[74:75], v[68:69], 0, s[4:5]
	s_mov_b64 s[4:5], 0x8000
	v_lshl_add_u64 v[76:77], v[68:69], 0, s[4:5]
	s_mov_b64 s[4:5], 0xa000
	v_lshl_add_u64 v[78:79], v[68:69], 0, s[4:5]
	s_mov_b64 s[4:5], 0xc000
	v_lshl_add_u64 v[80:81], v[68:69], 0, s[4:5]
	s_mov_b64 s[4:5], 0xe000
	v_lshl_add_u64 v[82:83], v[68:69], 0, s[4:5]
	s_mov_b64 s[4:5], 0x10000
	v_lshl_add_u64 v[84:85], v[68:69], 0, s[4:5]
	s_mov_b64 s[4:5], 0x12000
	v_lshl_add_u64 v[86:87], v[68:69], 0, s[4:5]
	s_mov_b64 s[4:5], 0x14000
	v_lshl_add_u64 v[88:89], v[68:69], 0, s[4:5]
	s_mov_b64 s[4:5], 0x16000
	v_lshl_add_u64 v[90:91], v[68:69], 0, s[4:5]
	s_mov_b64 s[4:5], 0x18000
	v_lshl_add_u64 v[92:93], v[68:69], 0, s[4:5]
	s_mov_b64 s[4:5], 0x1a000
	v_lshl_add_u64 v[94:95], v[68:69], 0, s[4:5]
	s_mov_b64 s[4:5], 0x1c000
	v_lshl_add_u64 v[96:97], v[68:69], 0, s[4:5]
	s_mov_b64 s[4:5], 0x1e000
	v_lshl_add_u64 v[98:99], v[68:69], 0, s[4:5]
	s_mov_b64 s[4:5], 0x20000
	v_lshl_add_u64 v[100:101], v[68:69], 0, s[4:5]
	s_mov_b64 s[4:5], 0x22000
	v_lshl_add_u64 v[102:103], v[68:69], 0, s[4:5]
	s_mov_b64 s[4:5], 0x24000
	v_lshl_add_u64 v[104:105], v[68:69], 0, s[4:5]
	s_mov_b64 s[4:5], 0x26000
	v_lshl_add_u64 v[106:107], v[68:69], 0, s[4:5]
	s_mov_b64 s[4:5], 0x28000
	v_lshl_add_u64 v[108:109], v[68:69], 0, s[4:5]
	s_mov_b64 s[4:5], 0x2a000
	v_lshl_add_u64 v[110:111], v[68:69], 0, s[4:5]
	s_mov_b64 s[4:5], 0x2c000
	v_lshl_add_u64 v[112:113], v[68:69], 0, s[4:5]
	s_mov_b64 s[4:5], 0x2e000
	v_lshl_add_u64 v[114:115], v[68:69], 0, s[4:5]
	s_mov_b64 s[4:5], 0x30000
	s_ashr_i32 s3, s2, 31
	v_lshl_add_u64 v[116:117], v[68:69], 0, s[4:5]
	s_mov_b64 s[4:5], 0x32000
	s_lshl_b64 s[2:3], s[2:3], 1
	v_lshl_add_u64 v[118:119], v[68:69], 0, s[4:5]
	s_mov_b64 s[4:5], 0x34000
	s_add_u32 s2, s22, s2
	v_lshl_add_u64 v[120:121], v[68:69], 0, s[4:5]
	s_mov_b64 s[4:5], 0x36000
	s_addc_u32 s3, s23, s3
	v_lshl_add_u64 v[122:123], v[68:69], 0, s[4:5]
	s_mov_b64 s[4:5], 0x38000
	v_lshl_add_u64 v[132:133], s[2:3], 0, v[138:139]
	s_mov_b64 s[2:3], 0x1400000
	v_lshl_add_u64 v[124:125], v[68:69], 0, s[4:5]
	s_mov_b64 s[4:5], 0x3a000
	v_lshl_add_u64 v[132:133], v[132:133], 0, s[2:3]
; #define GAS __attribute__((address_space(1)))
; #define LAS __attribute__((address_space(3)))
; #define LDS_WAIT() asm volatile("s_waitcnt lgkmcnt(0)" ::: "memory")
; __device__ __forceinline__ unsigned pk2(float lo, float hi) { return pg8::cvt_pk_bf16(lo, hi); }
; __device__ __forceinline__ void transpose_item(const float* W, int ldw, int K, bf16* WT, int k0, int n0, int dst0, LAS float* scr, int lane, const float* rowgain = nullptr) {
;     float v[32];
; #pragma unroll
;     for (int i = 0; i < 32; ++i) { const int kk = 2 * i + (lane >> 5); v[i] = __builtin_nontemporal_load(&W[(size_t)(k0 + kk) * ldw + n0 + (lane & 31)]); }
;     if (rowgain) {
; #pragma unroll
;         for (int i = 0; i < 32; ++i) v[i] *= rowgain[k0 + 2 * i + (lane >> 5)]; }
; #pragma unroll
;     for (int i = 0; i < 32; ++i) scr[(2 * i + (lane >> 5)) * 33 + (lane & 31)] = v[i];
;     LDS_WAIT(); asm volatile("" ::: "memory");
;     const int c = lane & 7;
; #pragma unroll
;     for (int j = 0; j < 4; ++j) { const int n = (lane >> 3) + 8 * j; const LAS float* s = scr + (8 * c) * 33 + n;
;         v4u o; o.x = pk2(s[0 * 33], s[1 * 33]); o.y = pk2(s[2 * 33], s[3 * 33]); o.z = pk2(s[4 * 33], s[5 * 33]); o.w = pk2(s[6 * 33], s[7 * 33]);
;         *(GAS v4u*)(WT + (size_t)(dst0 + n) * K + k0 + 8 * c) = o; }
; __device__ __forceinline__ void weight_unit(int wu, const Args& a, LAS unsigned char* lds, int wave, int lane) {
;     ...
;     for (int q = 0; q < 4; ++q) {
;         int r = wu * 32 + wave * 4 + q; if (r >= W_ITEMS) break;
	v_lshl_add_u64 v[136:137], s[22:23], 0, v[138:139]
	s_mov_b64 s[2:3], 0x900000
	v_add_u32_e32 v4, 2, v148
	v_add_u32_e32 v6, 4, v148
	v_add_u32_e32 v8, 6, v148
	v_add_u32_e32 v10, 8, v148
	v_add_u32_e32 v12, 10, v148
	v_add_u32_e32 v14, 12, v148
	v_add_u32_e32 v16, 14, v148
	v_add_u32_e32 v18, 16, v148
	v_add_u32_e32 v20, 18, v148
	v_add_u32_e32 v22, 20, v148
	v_add_u32_e32 v24, 22, v148
	v_add_u32_e32 v26, 24, v148
	v_add_u32_e32 v28, 26, v148
	v_add_u32_e32 v30, 28, v148
	v_add_u32_e32 v32, 30, v148
	v_add_u32_e32 v34, 32, v148
	v_add_u32_e32 v36, 34, v148
	v_add_u32_e32 v38, 36, v148
	v_add_u32_e32 v40, 38, v148
	v_add_u32_e32 v42, 40, v148
	v_add_u32_e32 v44, 42, v148
	v_add_u32_e32 v46, 44, v148
	v_add_u32_e32 v48, 46, v148
	v_add_u32_e32 v50, 48, v148
	v_add_u32_e32 v52, 50, v148
	v_add_u32_e32 v54, 52, v148
	v_add_u32_e32 v56, 54, v148
	v_add_u32_e32 v58, 56, v148
	v_add_u32_e32 v60, 58, v148
	v_add_u32_e32 v62, 60, v148
	v_add_u32_e32 v64, 62, v148
	v_lshl_add_u64 v[126:127], v[68:69], 0, s[4:5]
	s_mov_b64 s[4:5], 0x3c000
	v_lshl_add_u64 v[134:135], v[136:137], 0, s[2:3]
	s_mov_b64 s[2:3], 0x700000
	s_cmp_lg_u64 s[44:45], 0
	v_ashrrev_i32_e32 v149, 31, v148
	v_ashrrev_i32_e32 v5, 31, v4
	v_ashrrev_i32_e32 v7, 31, v6
	v_ashrrev_i32_e32 v9, 31, v8
	v_ashrrev_i32_e32 v11, 31, v10
	v_ashrrev_i32_e32 v13, 31, v12
	v_ashrrev_i32_e32 v15, 31, v14
	v_ashrrev_i32_e32 v17, 31, v16
	v_ashrrev_i32_e32 v19, 31, v18
	v_ashrrev_i32_e32 v21, 31, v20
	v_ashrrev_i32_e32 v23, 31, v22
	v_ashrrev_i32_e32 v25, 31, v24
	v_ashrrev_i32_e32 v27, 31, v26
	v_ashrrev_i32_e32 v29, 31, v28
	v_ashrrev_i32_e32 v31, 31, v30
	v_ashrrev_i32_e32 v33, 31, v32
	v_ashrrev_i32_e32 v35, 31, v34
	v_ashrrev_i32_e32 v37, 31, v36
	v_ashrrev_i32_e32 v39, 31, v38
	v_ashrrev_i32_e32 v41, 31, v40
	v_ashrrev_i32_e32 v43, 31, v42
	v_ashrrev_i32_e32 v45, 31, v44
	v_ashrrev_i32_e32 v47, 31, v46
	v_ashrrev_i32_e32 v49, 31, v48
	v_ashrrev_i32_e32 v51, 31, v50
	v_ashrrev_i32_e32 v53, 31, v52
	v_ashrrev_i32_e32 v55, 31, v54
	v_ashrrev_i32_e32 v57, 31, v56
	v_ashrrev_i32_e32 v59, 31, v58
	v_ashrrev_i32_e32 v61, 31, v60
	v_ashrrev_i32_e32 v63, 31, v62
	v_ashrrev_i32_e32 v65, 31, v64
	v_lshl_add_u64 v[128:129], v[68:69], 0, s[4:5]
	s_mov_b64 s[4:5], 0x3e000
	v_lshl_add_u64 v[136:137], v[136:137], 0, s[2:3]
	v_mov_b32_e32 v147, v139
	s_cselect_b64 s[2:3], -1, 0
	s_cmp_lg_u64 s[36:37], 0
	s_mov_b32 s1, 0
	v_lshlrev_b64 v[2:3], 12, v[148:149]
	v_lshlrev_b64 v[4:5], 12, v[4:5]
	v_lshlrev_b64 v[6:7], 12, v[6:7]
	v_lshlrev_b64 v[8:9], 12, v[8:9]
	v_lshlrev_b64 v[10:11], 12, v[10:11]
	v_lshlrev_b64 v[12:13], 12, v[12:13]
	v_lshlrev_b64 v[14:15], 12, v[14:15]
	v_lshlrev_b64 v[16:17], 12, v[16:17]
	v_lshlrev_b64 v[18:19], 12, v[18:19]
	v_lshlrev_b64 v[20:21], 12, v[20:21]
	v_lshlrev_b64 v[22:23], 12, v[22:23]
	v_lshlrev_b64 v[24:25], 12, v[24:25]
	v_lshlrev_b64 v[26:27], 12, v[26:27]
	v_lshlrev_b64 v[28:29], 12, v[28:29]
	v_lshlrev_b64 v[30:31], 12, v[30:31]
	v_lshlrev_b64 v[32:33], 12, v[32:33]
	v_lshlrev_b64 v[34:35], 12, v[34:35]
	v_lshlrev_b64 v[36:37], 12, v[36:37]
	v_lshlrev_b64 v[38:39], 12, v[38:39]
	v_lshlrev_b64 v[40:41], 12, v[40:41]
	v_lshlrev_b64 v[42:43], 12, v[42:43]
	v_lshlrev_b64 v[44:45], 12, v[44:45]
	v_lshlrev_b64 v[46:47], 12, v[46:47]
	v_lshlrev_b64 v[48:49], 12, v[48:49]
	v_lshlrev_b64 v[50:51], 12, v[50:51]
	v_lshlrev_b64 v[52:53], 12, v[52:53]
	v_lshlrev_b64 v[54:55], 12, v[54:55]
	v_lshlrev_b64 v[56:57], 12, v[56:57]
	v_lshlrev_b64 v[58:59], 12, v[58:59]
	v_lshlrev_b64 v[60:61], 12, v[60:61]
	v_lshlrev_b64 v[62:63], 12, v[62:63]
	v_lshlrev_b64 v[64:65], 12, v[64:65]
	v_add_u32_e32 v187, 8, v185
	v_add_u32_e32 v188, 16, v185
	v_add_u32_e32 v189, 24, v185
	v_lshl_add_u64 v[130:131], v[68:69], 0, s[4:5]
	v_lshl_add_u64 v[138:139], s[46:47], 0, v[146:147]
	v_lshl_add_u64 v[140:141], s[42:43], 0, v[146:147]
	v_lshl_add_u64 v[142:143], s[40:41], 0, v[146:147]
	v_lshl_add_u64 v[144:145], s[38:39], 0, v[146:147]
	v_lshl_add_u64 v[146:147], s[18:19], 0, v[146:147]
	v_lshl_add_u64 v[148:149], v[148:149], 2, s[44:45]
	s_cselect_b64 s[4:5], -1, 0
	s_lshl_b32 s11, s10, 5
	s_movk_i32 s12, 0x1600
	s_movk_i32 s13, 0x2c00
	s_mov_b32 s14, s52
	s_lshl_b32 s53, s52, 5
	s_add_i32 s11, s11, s53
	s_branch .LBB0_245

; __device__ __forceinline__ void weight_unit(int wu, const Args& a, LAS unsigned char* lds, int wave, int lane) {
;     ...
;     for (int q = 0; q < 4; ++q) {
;         int r = wu * 32 + wave * 4 + q; if (r >= W_ITEMS) break;
;         if (r < WI_OUT) { const int kb = r / 32, nb = r % 32; transpose_item(a.in[15], DM, DM, (bf16*)(ws + WS_WOUT), 64 * kb, 32 * nb, 32 * nb, scr, lane); continue; } r -= WI_OUT;
;         if (r < WI_G) { const int kb = r / 88, nb = r % 88, n0 = 32 * nb; transpose_item(a.in[17], FF, DM, (bf16*)(ws + WS_WGU), 64 * kb, n0, 256 * (n0 >> 7) + (n0 & 127), scr, lane, a.in[16]); continue; } r -= WI_G;
;         if (r < WI_G) { const int kb = r / 88, nb = r % 88, n0 = 32 * nb; transpose_item(a.in[18], FF, DM, (bf16*)(ws + WS_WGU), 64 * kb, n0, 256 * (n0 >> 7) + 128 + (n0 & 127), scr, lane, a.in[16]); continue; } r -= WI_G;
;         if (r < WI_DN) { const int kb = r / 32, nb = r % 32; transpose_item(a.in[19], DM, FF, (bf16*)(ws + WS_WDN), 64 * kb, 32 * nb, 32 * nb, scr, lane); continue; } r -= WI_DN;
;         { const int kb = r / 32, nb = r % 32; transpose_item(a.in[21], DM, DM, (bf16*)(ws + WS_WPG), 64 * kb, 32 * nb, 32 * nb, scr, lane, a.in[20]); }
;     }
.LBB0_271:
	s_add_i32 s14, s14, 1
	s_add_i32 s11, s11, 32
	s_cmp_eq_u32 s14, s35
	s_cselect_b64 s[6:7], -1, 0
	s_branch .LBB0_244
.LBB0_272:
	s_cmp_lg_u32 s54, 0
	s_cbranch_scc1 .Lwu_done
	s_cmp_gt_u32 s32, 127
	s_cbranch_scc1 .Lwu_done
	s_mov_b32 s54, 1
	s_and_b32 s52, s32, 3
	s_add_i32 s35, s52, 1
	s_lshr_b32 s0, s32, 2
	s_addk_i32 s0, 0x80
	s_branch .Lwu_again
